# one static priority raise (s_setprio 2) for waves 4-7 for the duration of the selected-attention block loop, so the two waves of a SIMD fall into alternating MFMA / VALU phases
# speedup vs baseline: 1.0139x; 1.0091x over previous
.LBB0_1549:
.LBB0_1550:
	v_readfirstlane_b32 s46, v70
	v_readfirstlane_b32 s47, v71
	v_readfirstlane_b32 s62, v72
	v_readfirstlane_b32 s63, v73
	v_and_b32_e32 v248, 15, v181
	v_lshrrev_b32_e32 v249, 4, v181
	v_lshrrev_b32_e32 v248, 2, v248
	v_lshlrev_b32_e32 v249, 2, v249
	v_readlane_b32 s23, v243, 32
	v_mov_b32_e32 v244, 1
	v_lshlrev_b32_e32 v244, v248, v244
	s_mov_b32 s16, 0x3e38aa3b
	s_mov_b32 s17, 0x3e38aa3b
	v_lshlrev_b32_e32 v79, 4, v181
	s_add_i32 s23, s23, s97
	v_add_u32_e32 v247, s23, v248
	v_mad_u64_u32 v[250:251], s[50:51], v247, v212, v[68:69]
	global_load_dwordx4 v[100:103], v[250:251], off
	global_load_dwordx4 v[104:107], v[250:251], off offset:64
	v_add_u32_e32 v249, 4, v247
	v_mad_u64_u32 v[250:251], s[50:51], v249, v212, v[68:69]
	global_load_dwordx4 v[108:111], v[250:251], off
	global_load_dwordx4 v[112:115], v[250:251], off offset:64
	v_add_u32_e32 v249, 8, v247
	v_mad_u64_u32 v[250:251], s[50:51], v249, v212, v[68:69]
	global_load_dwordx4 v[116:119], v[250:251], off
	global_load_dwordx4 v[120:123], v[250:251], off offset:64
	v_add_u32_e32 v249, 12, v247
	v_mad_u64_u32 v[250:251], s[50:51], v249, v212, v[68:69]
	global_load_dwordx4 v[124:127], v[250:251], off
	global_load_dwordx4 v[128:131], v[250:251], off offset:64
	v_and_b32_e32 v248, 15, v181
	v_lshrrev_b32_e32 v249, 4, v181
	v_lshlrev_b32_e32 v198, 6, v248
	v_lshl_add_u32 v198, v249, 2, v198
	v_add_u32_e32 v198, s96, v198
	v_lshl_add_u32 v199, v248, 2, s96
	ds_read_b32 v12, v198 offset:16384
	ds_read_b32 v13, v198 offset:16400
	ds_read_b32 v14, v198 offset:16416
	ds_read_b32 v15, v198 offset:16432
	ds_read_b32 v16, v199 offset:17408
	v_lshl_add_u32 v199, v181, 2, s96
	v_mov_b32_e32 v17, 1
	v_lshlrev_b32_e32 v17, v248, v17
	s_waitcnt lgkmcnt(0)
	v_mul_f32_e32 v81, 0x3fb8aa3b, v81
	ds_write_b32 v199, v11 offset:16384
	ds_write_b32 v199, v11 offset:16640
	ds_write_b32 v199, v11 offset:16896
	ds_write_b32 v199, v11 offset:17152
	v_cmp_lt_i32_e32 vcc, v249, v16
	v_and_b32_e32 v12, 0xff, v12
	v_lshl_add_u32 v12, v12, 2, s96
	v_cndmask_b32_e32 v18, 0, v17, vcc
	ds_or_b32 v12, v18 offset:16384
	v_add_u32_e32 v18, 4, v249
	v_cmp_lt_i32_e32 vcc, v18, v16
	v_and_b32_e32 v13, 0xff, v13
	v_lshl_add_u32 v13, v13, 2, s96
	v_cndmask_b32_e32 v18, 0, v17, vcc
	ds_or_b32 v13, v18 offset:16384
	v_add_u32_e32 v18, 8, v249
	v_cmp_lt_i32_e32 vcc, v18, v16
	v_and_b32_e32 v14, 0xff, v14
	v_lshl_add_u32 v14, v14, 2, s96
	v_cndmask_b32_e32 v18, 0, v17, vcc
	ds_or_b32 v14, v18 offset:16384
	v_add_u32_e32 v18, 12, v249
	v_cmp_lt_i32_e32 vcc, v18, v16
	v_and_b32_e32 v15, 0xff, v15
	v_lshl_add_u32 v15, v15, 2, s96
	v_cndmask_b32_e32 v18, 0, v17, vcc
	ds_or_b32 v15, v18 offset:16384
	s_waitcnt lgkmcnt(0)
	ds_read_b32 v12, v199 offset:16384
	ds_read_b32 v13, v199 offset:16640
	ds_read_b32 v14, v199 offset:16896
	ds_read_b32 v15, v199 offset:17152
	s_mov_b32 s25, 0
	s_waitcnt lgkmcnt(0)
	v_cmp_ne_u32_e64 s[4:5], 0, v12
	v_lshlrev_b32_e32 v16, 16, v12
	v_add_u32_e32 v17, 0, v181
	v_or_b32_e32 v16, v16, v17
	v_mbcnt_lo_u32_b32 v17, s4, 0
	v_mbcnt_hi_u32_b32 v17, s5, v17
	v_add_u32_e32 v17, s25, v17
	v_lshl_add_u32 v17, v17, 2, s96
	v_add_u32_e32 v17, 0x4000, v17
	v_add_u32_e32 v18, 0x4400, v199
	s_bcnt1_i32_b64 s13, s[4:5]
	v_cndmask_b32_e64 v17, v18, v17, s[4:5]
	s_add_i32 s25, s25, s13
	ds_write_b32 v17, v16
	v_cmp_ne_u32_e64 s[4:5], 0, v13
	v_lshlrev_b32_e32 v16, 16, v13
	v_add_u32_e32 v17, 64, v181
	v_or_b32_e32 v16, v16, v17
	v_mbcnt_lo_u32_b32 v17, s4, 0
	v_mbcnt_hi_u32_b32 v17, s5, v17
	v_add_u32_e32 v17, s25, v17
	v_lshl_add_u32 v17, v17, 2, s96
	v_add_u32_e32 v17, 0x4000, v17
	v_add_u32_e32 v18, 0x4400, v199
	s_bcnt1_i32_b64 s13, s[4:5]
	v_cndmask_b32_e64 v17, v18, v17, s[4:5]
	s_add_i32 s25, s25, s13
	ds_write_b32 v17, v16
	v_cmp_ne_u32_e64 s[4:5], 0, v14
	v_lshlrev_b32_e32 v16, 16, v14
	v_add_u32_e32 v17, 128, v181
	v_or_b32_e32 v16, v16, v17
	v_mbcnt_lo_u32_b32 v17, s4, 0
	v_mbcnt_hi_u32_b32 v17, s5, v17
	v_add_u32_e32 v17, s25, v17
	v_lshl_add_u32 v17, v17, 2, s96
	v_add_u32_e32 v17, 0x4000, v17
	v_add_u32_e32 v18, 0x4400, v199
	s_bcnt1_i32_b64 s13, s[4:5]
	v_cndmask_b32_e64 v17, v18, v17, s[4:5]
	s_add_i32 s25, s25, s13
	ds_write_b32 v17, v16
	v_cmp_ne_u32_e64 s[4:5], 0, v15
	v_lshlrev_b32_e32 v16, 16, v15
	v_add_u32_e32 v17, 192, v181
	v_or_b32_e32 v16, v16, v17
	v_mbcnt_lo_u32_b32 v17, s4, 0
	v_mbcnt_hi_u32_b32 v17, s5, v17
	v_add_u32_e32 v17, s25, v17
	v_lshl_add_u32 v17, v17, 2, s96
	v_add_u32_e32 v17, 0x4000, v17
	v_add_u32_e32 v18, 0x4400, v199
	s_bcnt1_i32_b64 s13, s[4:5]
	v_cndmask_b32_e64 v17, v18, v17, s[4:5]
	s_add_i32 s25, s25, s13
	ds_write_b32 v17, v16
	s_waitcnt vmcnt(0)
	v_lshlrev_b32_e32 v245, 16, v100
	v_and_b32_e32 v246, 0xffff0000, v100
	v_mul_f32_e32 v245, 0x41000000, v245
	v_mul_f32_e32 v246, 0x41000000, v246
	v_lshlrev_b32_e32 v248, 16, v101
	v_and_b32_e32 v249, 0xffff0000, v101
	v_cvt_pk_fp8_f32 v164, v245, v246
	v_mul_f32_e32 v248, 0x41000000, v248
	v_mul_f32_e32 v249, 0x41000000, v249
	s_nop 0
	v_cvt_pk_fp8_f32 v164, v248, v249 op_sel:[0,0,1]
	v_lshlrev_b32_e32 v245, 16, v102
	v_and_b32_e32 v246, 0xffff0000, v102
	v_mul_f32_e32 v245, 0x41000000, v245
	v_mul_f32_e32 v246, 0x41000000, v246
	v_lshlrev_b32_e32 v248, 16, v103
	v_and_b32_e32 v249, 0xffff0000, v103
	v_cvt_pk_fp8_f32 v165, v245, v246
	v_mul_f32_e32 v248, 0x41000000, v248
	v_mul_f32_e32 v249, 0x41000000, v249
	s_nop 0
	v_cvt_pk_fp8_f32 v165, v248, v249 op_sel:[0,0,1]
	v_lshlrev_b32_e32 v245, 16, v104
	v_and_b32_e32 v246, 0xffff0000, v104
	v_mul_f32_e32 v245, 0x41000000, v245
	v_mul_f32_e32 v246, 0x41000000, v246
	v_lshlrev_b32_e32 v248, 16, v105
	v_and_b32_e32 v249, 0xffff0000, v105
	v_cvt_pk_fp8_f32 v166, v245, v246
	v_mul_f32_e32 v248, 0x41000000, v248
	v_mul_f32_e32 v249, 0x41000000, v249
	s_nop 0
	v_cvt_pk_fp8_f32 v166, v248, v249 op_sel:[0,0,1]
	v_lshlrev_b32_e32 v245, 16, v106
	v_and_b32_e32 v246, 0xffff0000, v106
	v_mul_f32_e32 v245, 0x41000000, v245
	v_mul_f32_e32 v246, 0x41000000, v246
	v_lshlrev_b32_e32 v248, 16, v107
	v_and_b32_e32 v249, 0xffff0000, v107
	v_cvt_pk_fp8_f32 v167, v245, v246
	v_mul_f32_e32 v248, 0x41000000, v248
	v_mul_f32_e32 v249, 0x41000000, v249
	s_nop 0
	v_cvt_pk_fp8_f32 v167, v248, v249 op_sel:[0,0,1]
	v_lshlrev_b32_e32 v245, 16, v108
	v_and_b32_e32 v246, 0xffff0000, v108
	v_mul_f32_e32 v245, 0x41000000, v245
	v_mul_f32_e32 v246, 0x41000000, v246
	v_lshlrev_b32_e32 v248, 16, v109
	v_and_b32_e32 v249, 0xffff0000, v109
	v_cvt_pk_fp8_f32 v168, v245, v246
	v_mul_f32_e32 v248, 0x41000000, v248
	v_mul_f32_e32 v249, 0x41000000, v249
	s_nop 0
	v_cvt_pk_fp8_f32 v168, v248, v249 op_sel:[0,0,1]
	v_lshlrev_b32_e32 v245, 16, v110
	v_and_b32_e32 v246, 0xffff0000, v110
	v_mul_f32_e32 v245, 0x41000000, v245
	v_mul_f32_e32 v246, 0x41000000, v246
	v_lshlrev_b32_e32 v248, 16, v111
	v_and_b32_e32 v249, 0xffff0000, v111
	v_cvt_pk_fp8_f32 v169, v245, v246
	v_mul_f32_e32 v248, 0x41000000, v248
	v_mul_f32_e32 v249, 0x41000000, v249
	s_nop 0
	v_cvt_pk_fp8_f32 v169, v248, v249 op_sel:[0,0,1]
	v_lshlrev_b32_e32 v245, 16, v112
	v_and_b32_e32 v246, 0xffff0000, v112
	v_mul_f32_e32 v245, 0x41000000, v245
	v_mul_f32_e32 v246, 0x41000000, v246
	v_lshlrev_b32_e32 v248, 16, v113
	v_and_b32_e32 v249, 0xffff0000, v113
	v_cvt_pk_fp8_f32 v170, v245, v246
	v_mul_f32_e32 v248, 0x41000000, v248
	v_mul_f32_e32 v249, 0x41000000, v249
	s_nop 0
	v_cvt_pk_fp8_f32 v170, v248, v249 op_sel:[0,0,1]
	v_lshlrev_b32_e32 v245, 16, v114
	v_and_b32_e32 v246, 0xffff0000, v114
	v_mul_f32_e32 v245, 0x41000000, v245
	v_mul_f32_e32 v246, 0x41000000, v246
	v_lshlrev_b32_e32 v248, 16, v115
	v_and_b32_e32 v249, 0xffff0000, v115
	v_cvt_pk_fp8_f32 v171, v245, v246
	v_mul_f32_e32 v248, 0x41000000, v248
	v_mul_f32_e32 v249, 0x41000000, v249
	s_nop 0
	v_cvt_pk_fp8_f32 v171, v248, v249 op_sel:[0,0,1]
	v_lshlrev_b32_e32 v245, 16, v116
	v_and_b32_e32 v246, 0xffff0000, v116
	v_mul_f32_e32 v245, 0x41000000, v245
	v_mul_f32_e32 v246, 0x41000000, v246
	v_lshlrev_b32_e32 v248, 16, v117
	v_and_b32_e32 v249, 0xffff0000, v117
	v_cvt_pk_fp8_f32 v182, v245, v246
	v_mul_f32_e32 v248, 0x41000000, v248
	v_mul_f32_e32 v249, 0x41000000, v249
	s_nop 0
	v_cvt_pk_fp8_f32 v182, v248, v249 op_sel:[0,0,1]
	v_lshlrev_b32_e32 v245, 16, v118
	v_and_b32_e32 v246, 0xffff0000, v118
	v_mul_f32_e32 v245, 0x41000000, v245
	v_mul_f32_e32 v246, 0x41000000, v246
	v_lshlrev_b32_e32 v248, 16, v119
	v_and_b32_e32 v249, 0xffff0000, v119
	v_cvt_pk_fp8_f32 v183, v245, v246
	v_mul_f32_e32 v248, 0x41000000, v248
	v_mul_f32_e32 v249, 0x41000000, v249
	s_nop 0
	v_cvt_pk_fp8_f32 v183, v248, v249 op_sel:[0,0,1]
	v_lshlrev_b32_e32 v245, 16, v120
	v_and_b32_e32 v246, 0xffff0000, v120
	v_mul_f32_e32 v245, 0x41000000, v245
	v_mul_f32_e32 v246, 0x41000000, v246
	v_lshlrev_b32_e32 v248, 16, v121
	v_and_b32_e32 v249, 0xffff0000, v121
	v_cvt_pk_fp8_f32 v184, v245, v246
	v_mul_f32_e32 v248, 0x41000000, v248
	v_mul_f32_e32 v249, 0x41000000, v249
	s_nop 0
	v_cvt_pk_fp8_f32 v184, v248, v249 op_sel:[0,0,1]
	v_lshlrev_b32_e32 v245, 16, v122
	v_and_b32_e32 v246, 0xffff0000, v122
	v_mul_f32_e32 v245, 0x41000000, v245
	v_mul_f32_e32 v246, 0x41000000, v246
	v_lshlrev_b32_e32 v248, 16, v123
	v_and_b32_e32 v249, 0xffff0000, v123
	v_cvt_pk_fp8_f32 v185, v245, v246
	v_mul_f32_e32 v248, 0x41000000, v248
	v_mul_f32_e32 v249, 0x41000000, v249
	s_nop 0
	v_cvt_pk_fp8_f32 v185, v248, v249 op_sel:[0,0,1]
	v_lshlrev_b32_e32 v245, 16, v124
	v_and_b32_e32 v246, 0xffff0000, v124
	v_mul_f32_e32 v245, 0x41000000, v245
	v_mul_f32_e32 v246, 0x41000000, v246
	v_lshlrev_b32_e32 v248, 16, v125
	v_and_b32_e32 v249, 0xffff0000, v125
	v_cvt_pk_fp8_f32 v186, v245, v246
	v_mul_f32_e32 v248, 0x41000000, v248
	v_mul_f32_e32 v249, 0x41000000, v249
	s_nop 0
	v_cvt_pk_fp8_f32 v186, v248, v249 op_sel:[0,0,1]
	v_lshlrev_b32_e32 v245, 16, v126
	v_and_b32_e32 v246, 0xffff0000, v126
	v_mul_f32_e32 v245, 0x41000000, v245
	v_mul_f32_e32 v246, 0x41000000, v246
	v_lshlrev_b32_e32 v248, 16, v127
	v_and_b32_e32 v249, 0xffff0000, v127
	v_cvt_pk_fp8_f32 v187, v245, v246
	v_mul_f32_e32 v248, 0x41000000, v248
	v_mul_f32_e32 v249, 0x41000000, v249
	s_nop 0
	v_cvt_pk_fp8_f32 v187, v248, v249 op_sel:[0,0,1]
	v_lshlrev_b32_e32 v245, 16, v128
	v_and_b32_e32 v246, 0xffff0000, v128
	v_mul_f32_e32 v245, 0x41000000, v245
	v_mul_f32_e32 v246, 0x41000000, v246
	v_lshlrev_b32_e32 v248, 16, v129
	v_and_b32_e32 v249, 0xffff0000, v129
	v_cvt_pk_fp8_f32 v188, v245, v246
	v_mul_f32_e32 v248, 0x41000000, v248
	v_mul_f32_e32 v249, 0x41000000, v249
	s_nop 0
	v_cvt_pk_fp8_f32 v188, v248, v249 op_sel:[0,0,1]
	v_lshlrev_b32_e32 v245, 16, v130
	v_and_b32_e32 v246, 0xffff0000, v130
	v_mul_f32_e32 v245, 0x41000000, v245
	v_mul_f32_e32 v246, 0x41000000, v246
	v_lshlrev_b32_e32 v248, 16, v131
	v_and_b32_e32 v249, 0xffff0000, v131
	v_cvt_pk_fp8_f32 v189, v245, v246
	v_mul_f32_e32 v248, 0x41000000, v248
	v_mul_f32_e32 v249, 0x41000000, v249
	s_nop 0
	v_cvt_pk_fp8_f32 v189, v248, v249 op_sel:[0,0,1]
	v_mov_b64_e32 v[100:101], 0
	v_mov_b64_e32 v[102:103], 0
	v_mov_b64_e32 v[104:105], 0
	v_mov_b64_e32 v[106:107], 0
	v_mov_b64_e32 v[108:109], 0
	v_mov_b64_e32 v[110:111], 0
	v_mov_b64_e32 v[112:113], 0
	v_mov_b64_e32 v[114:115], 0
	v_mov_b32_e32 v190, 0
	v_mov_b32_e32 v194, 0
	v_mov_b64_e32 v[116:117], 0
	v_mov_b64_e32 v[118:119], 0
	v_mov_b64_e32 v[120:121], 0
	v_mov_b64_e32 v[122:123], 0
	v_mov_b64_e32 v[124:125], 0
	v_mov_b64_e32 v[126:127], 0
	v_mov_b64_e32 v[128:129], 0
	v_mov_b64_e32 v[130:131], 0
	v_mov_b32_e32 v191, 0
	v_mov_b32_e32 v195, 0
	v_mov_b64_e32 v[132:133], 0
	v_mov_b64_e32 v[134:135], 0
	v_mov_b64_e32 v[136:137], 0
	v_mov_b64_e32 v[138:139], 0
	v_mov_b64_e32 v[140:141], 0
	v_mov_b64_e32 v[142:143], 0
	v_mov_b64_e32 v[144:145], 0
	v_mov_b64_e32 v[146:147], 0
	v_mov_b32_e32 v192, 0
	v_mov_b32_e32 v196, 0
	v_mov_b64_e32 v[148:149], 0
	v_mov_b64_e32 v[150:151], 0
	v_mov_b64_e32 v[152:153], 0
	v_mov_b64_e32 v[154:155], 0
	v_mov_b64_e32 v[156:157], 0
	v_mov_b64_e32 v[158:159], 0
	v_mov_b64_e32 v[160:161], 0
	v_mov_b64_e32 v[162:163], 0
	v_mov_b32_e32 v193, 0
	v_mov_b32_e32 v197, 0
	v_mov_b32_e32 v77, 0xff800000
	v_mov_b32_e32 v78, 0xff800000
	s_waitcnt lgkmcnt(0)
	s_mov_b32 s35, 0
	s_lshl_b32 s13, s35, 2
	s_add_i32 s13, s13, s96
	v_mov_b32_e32 v76, s13
	ds_read_b32 v76, v76 offset:16384
	s_add_i32 s14, s25, -1
	s_min_i32 s14, s14, 1
	s_waitcnt lgkmcnt(0)
	v_readfirstlane_b32 s13, v76
	s_and_b32 s54, s13, 0xffff
	s_lshr_b32 s48, s13, 16
	s_lshl_b32 s13, s14, 2
	s_add_i32 s13, s13, s96
	v_mov_b32_e32 v76, s13
	ds_read_b32 v76, v76 offset:16384
	s_lshl_b32 s12, s54, 12
	s_add_u32 s30, s46, s12
	s_addc_u32 s31, s47, 0
	global_load_dwordx4 v[2:5], v79, s[30:31]
	global_load_dwordx4 v[6:9], v79, s[30:31] offset:1024
	global_load_dwordx4 v[12:15], v79, s[30:31] offset:2048
	global_load_dwordx4 v[16:19], v79, s[30:31] offset:3072
	s_lshl_b32 s12, s54, 12
	s_add_u32 s30, s62, s12
	s_addc_u32 s31, s63, 0
	global_load_dwordx4 v[36:39], v79, s[30:31]
	global_load_dwordx4 v[40:43], v79, s[30:31] offset:1024
	global_load_dwordx4 v[44:47], v79, s[30:31] offset:2048
	global_load_dwordx4 v[48:51], v79, s[30:31] offset:3072
	s_waitcnt lgkmcnt(0)
	v_readfirstlane_b32 s13, v76
	s_and_b32 s15, s13, 0xffff
	s_lshr_b32 s27, s13, 16
	s_add_i32 s83, s25, -1
	s_min_i32 s83, s83, 2
	s_lshl_b32 s83, s83, 2
	s_add_i32 s83, s83, s96
	v_mov_b32_e32 v76, s83
	ds_read_b32 v76, v76 offset:16384
	s_lshl_b32 s83, s15, 12
	s_add_u32 s30, s46, s83
	s_addc_u32 s31, s47, 0
	global_load_dwordx4 v[20:23], v79, s[30:31]
	global_load_dwordx4 v[24:27], v79, s[30:31] offset:1024
	global_load_dwordx4 v[28:31], v79, s[30:31] offset:2048
	global_load_dwordx4 v[32:35], v79, s[30:31] offset:3072
	s_waitcnt lgkmcnt(0)
	v_readfirstlane_b32 s13, v76
	s_and_b32 s32, s13, 0xffff
	s_lshr_b32 s55, s13, 16
	v_readfirstlane_b32 s83, v1
	s_bitcmp1_b32 s83, 8
	s_cbranch_scc0 .Lbm2_nostag
	s_setprio 2
	s_sleep 4

.Lbm2_done:
	s_setprio 0
	s_waitcnt vmcnt(0)
	v_and_b32_e32 v245, 15, v181
	v_lshrrev_b32_e32 v246, 4, v181
	v_lshrrev_b32_e32 v247, 2, v245
	v_add_u32_e32 v247, s23, v247
	v_lshlrev_b32_e32 v245, 8, v245
	v_lshl_add_u32 v245, v246, 4, v245
	v_add_u32_e32 v200, s96, v245
	v_mad_u64_u32 v[250:251], s[50:51], v247, v213, v[74:75]
	global_load_dword v252, v[250:251], off offset:4
	v_add_u32_e32 v246, 4, v247
	v_mad_u64_u32 v[250:251], s[50:51], v246, v213, v[74:75]
	global_load_dword v253, v[250:251], off offset:4
	v_add_u32_e32 v246, 8, v247
	v_mad_u64_u32 v[250:251], s[50:51], v246, v213, v[74:75]
	global_load_dword v254, v[250:251], off offset:4
	v_add_u32_e32 v246, 12, v247
	v_mad_u64_u32 v[250:251], s[50:51], v246, v213, v[74:75]
	global_load_dword v255, v[250:251], off offset:4
	v_mov_b32_e32 v199, v194
	s_nop 1
	v_permlane16_swap_b32_e32 v194, v199
	s_nop 0
	v_add_f32_e32 v194, v194, v199
	v_mov_b32_e32 v199, v194
	s_nop 1
	v_permlane32_swap_b32_e32 v194, v199
	s_nop 0
	v_add_f32_e32 v194, v194, v199
	v_max_f32_e32 v194, 0xda24260, v194
	v_mov_b32_e32 v199, v195
	s_nop 1
	v_permlane16_swap_b32_e32 v195, v199
	s_nop 0
	v_add_f32_e32 v195, v195, v199
	v_mov_b32_e32 v199, v195
	s_nop 1
	v_permlane32_swap_b32_e32 v195, v199
	s_nop 0
	v_add_f32_e32 v195, v195, v199
	v_max_f32_e32 v195, 0xda24260, v195
	v_mov_b32_e32 v199, v196
	s_nop 1
	v_permlane16_swap_b32_e32 v196, v199
	s_nop 0
	v_add_f32_e32 v196, v196, v199
	v_mov_b32_e32 v199, v196
	s_nop 1
	v_permlane32_swap_b32_e32 v196, v199
	s_nop 0
	v_add_f32_e32 v196, v196, v199
	v_max_f32_e32 v196, 0xda24260, v196
	v_mov_b32_e32 v199, v197
	s_nop 1
	v_permlane16_swap_b32_e32 v197, v199
	s_nop 0
	v_add_f32_e32 v197, v197, v199
	v_mov_b32_e32 v199, v197
	s_nop 1
	v_permlane32_swap_b32_e32 v197, v199
	s_nop 0
	v_add_f32_e32 v197, v197, v199
	v_max_f32_e32 v197, 0xda24260, v197
	s_waitcnt vmcnt(0)
	v_div_scale_f32 v2, s[50:51], v194, v194, v252
	v_rcp_f32_e32 v3, v2
	s_nop 0
	v_fma_f32 v4, -v2, v3, 1.0
	v_fmac_f32_e32 v3, v4, v3
	v_div_scale_f32 v4, vcc, v252, v194, v252
	v_mul_f32_e32 v5, v4, v3
	v_fma_f32 v6, -v2, v5, v4
	v_fmac_f32_e32 v5, v6, v3
	v_fma_f32 v2, -v2, v5, v4
	v_div_fmas_f32 v2, v2, v3, v5
	v_div_fixup_f32 v248, v2, v194, v252
	ds_read_b128 v[16:19], v200 offset:0
	s_waitcnt lgkmcnt(0)
	v_pk_fma_f32 v[100:101], v[100:101], v[248:249], v[16:17] op_sel_hi:[1,0,1]
	v_pk_fma_f32 v[102:103], v[102:103], v[248:249], v[18:19] op_sel_hi:[1,0,1]
	ds_write_b128 v200, v[100:103] offset:0
	ds_read_b128 v[16:19], v200 offset:64
	s_waitcnt lgkmcnt(0)
	v_pk_fma_f32 v[104:105], v[104:105], v[248:249], v[16:17] op_sel_hi:[1,0,1]
	v_pk_fma_f32 v[106:107], v[106:107], v[248:249], v[18:19] op_sel_hi:[1,0,1]
	ds_write_b128 v200, v[104:107] offset:64
	ds_read_b128 v[16:19], v200 offset:128
	s_waitcnt lgkmcnt(0)
	v_pk_fma_f32 v[108:109], v[108:109], v[248:249], v[16:17] op_sel_hi:[1,0,1]
	v_pk_fma_f32 v[110:111], v[110:111], v[248:249], v[18:19] op_sel_hi:[1,0,1]
	ds_write_b128 v200, v[108:111] offset:128
	ds_read_b128 v[16:19], v200 offset:192
	s_waitcnt lgkmcnt(0)
	v_pk_fma_f32 v[112:113], v[112:113], v[248:249], v[16:17] op_sel_hi:[1,0,1]
	v_pk_fma_f32 v[114:115], v[114:115], v[248:249], v[18:19] op_sel_hi:[1,0,1]
	ds_write_b128 v200, v[112:115] offset:192
	v_div_scale_f32 v2, s[50:51], v195, v195, v253
	v_rcp_f32_e32 v3, v2
	s_nop 0
	v_fma_f32 v4, -v2, v3, 1.0
	v_fmac_f32_e32 v3, v4, v3
	v_div_scale_f32 v4, vcc, v253, v195, v253
	v_mul_f32_e32 v5, v4, v3
	v_fma_f32 v6, -v2, v5, v4
	v_fmac_f32_e32 v5, v6, v3
	v_fma_f32 v2, -v2, v5, v4
	v_div_fmas_f32 v2, v2, v3, v5
	v_div_fixup_f32 v248, v2, v195, v253
	ds_read_b128 v[16:19], v200 offset:4096
	s_waitcnt lgkmcnt(0)
	v_pk_fma_f32 v[116:117], v[116:117], v[248:249], v[16:17] op_sel_hi:[1,0,1]
	v_pk_fma_f32 v[118:119], v[118:119], v[248:249], v[18:19] op_sel_hi:[1,0,1]
	ds_write_b128 v200, v[116:119] offset:4096
	ds_read_b128 v[16:19], v200 offset:4160
	s_waitcnt lgkmcnt(0)
	v_pk_fma_f32 v[120:121], v[120:121], v[248:249], v[16:17] op_sel_hi:[1,0,1]
	v_pk_fma_f32 v[122:123], v[122:123], v[248:249], v[18:19] op_sel_hi:[1,0,1]
	ds_write_b128 v200, v[120:123] offset:4160
	ds_read_b128 v[16:19], v200 offset:4224
	s_waitcnt lgkmcnt(0)
	v_pk_fma_f32 v[124:125], v[124:125], v[248:249], v[16:17] op_sel_hi:[1,0,1]
	v_pk_fma_f32 v[126:127], v[126:127], v[248:249], v[18:19] op_sel_hi:[1,0,1]
	ds_write_b128 v200, v[124:127] offset:4224
	ds_read_b128 v[16:19], v200 offset:4288
	s_waitcnt lgkmcnt(0)
	v_pk_fma_f32 v[128:129], v[128:129], v[248:249], v[16:17] op_sel_hi:[1,0,1]
	v_pk_fma_f32 v[130:131], v[130:131], v[248:249], v[18:19] op_sel_hi:[1,0,1]
	ds_write_b128 v200, v[128:131] offset:4288
	v_div_scale_f32 v2, s[50:51], v196, v196, v254
	v_rcp_f32_e32 v3, v2
	s_nop 0
	v_fma_f32 v4, -v2, v3, 1.0
	v_fmac_f32_e32 v3, v4, v3
	v_div_scale_f32 v4, vcc, v254, v196, v254
	v_mul_f32_e32 v5, v4, v3
	v_fma_f32 v6, -v2, v5, v4
	v_fmac_f32_e32 v5, v6, v3
	v_fma_f32 v2, -v2, v5, v4
	v_div_fmas_f32 v2, v2, v3, v5
	v_div_fixup_f32 v248, v2, v196, v254
	ds_read_b128 v[16:19], v200 offset:8192
	s_waitcnt lgkmcnt(0)
	v_pk_fma_f32 v[132:133], v[132:133], v[248:249], v[16:17] op_sel_hi:[1,0,1]
	v_pk_fma_f32 v[134:135], v[134:135], v[248:249], v[18:19] op_sel_hi:[1,0,1]
	ds_write_b128 v200, v[132:135] offset:8192
	ds_read_b128 v[16:19], v200 offset:8256
	s_waitcnt lgkmcnt(0)
	v_pk_fma_f32 v[136:137], v[136:137], v[248:249], v[16:17] op_sel_hi:[1,0,1]
	v_pk_fma_f32 v[138:139], v[138:139], v[248:249], v[18:19] op_sel_hi:[1,0,1]
	ds_write_b128 v200, v[136:139] offset:8256
	ds_read_b128 v[16:19], v200 offset:8320
	s_waitcnt lgkmcnt(0)
	v_pk_fma_f32 v[140:141], v[140:141], v[248:249], v[16:17] op_sel_hi:[1,0,1]
	v_pk_fma_f32 v[142:143], v[142:143], v[248:249], v[18:19] op_sel_hi:[1,0,1]
	ds_write_b128 v200, v[140:143] offset:8320
	ds_read_b128 v[16:19], v200 offset:8384
	s_waitcnt lgkmcnt(0)
	v_pk_fma_f32 v[144:145], v[144:145], v[248:249], v[16:17] op_sel_hi:[1,0,1]
	v_pk_fma_f32 v[146:147], v[146:147], v[248:249], v[18:19] op_sel_hi:[1,0,1]
	ds_write_b128 v200, v[144:147] offset:8384
	v_div_scale_f32 v2, s[50:51], v197, v197, v255
	v_rcp_f32_e32 v3, v2
	s_nop 0
	v_fma_f32 v4, -v2, v3, 1.0
	v_fmac_f32_e32 v3, v4, v3
	v_div_scale_f32 v4, vcc, v255, v197, v255
	v_mul_f32_e32 v5, v4, v3
	v_fma_f32 v6, -v2, v5, v4
	v_fmac_f32_e32 v5, v6, v3
	v_fma_f32 v2, -v2, v5, v4
	v_div_fmas_f32 v2, v2, v3, v5
	v_div_fixup_f32 v248, v2, v197, v255
	ds_read_b128 v[16:19], v200 offset:12288
	s_waitcnt lgkmcnt(0)
	v_pk_fma_f32 v[148:149], v[148:149], v[248:249], v[16:17] op_sel_hi:[1,0,1]
	v_pk_fma_f32 v[150:151], v[150:151], v[248:249], v[18:19] op_sel_hi:[1,0,1]
	ds_write_b128 v200, v[148:151] offset:12288
	ds_read_b128 v[16:19], v200 offset:12352
	s_waitcnt lgkmcnt(0)
	v_pk_fma_f32 v[152:153], v[152:153], v[248:249], v[16:17] op_sel_hi:[1,0,1]
	v_pk_fma_f32 v[154:155], v[154:155], v[248:249], v[18:19] op_sel_hi:[1,0,1]
	ds_write_b128 v200, v[152:155] offset:12352
	ds_read_b128 v[16:19], v200 offset:12416
	s_waitcnt lgkmcnt(0)
	v_pk_fma_f32 v[156:157], v[156:157], v[248:249], v[16:17] op_sel_hi:[1,0,1]
	v_pk_fma_f32 v[158:159], v[158:159], v[248:249], v[18:19] op_sel_hi:[1,0,1]
	ds_write_b128 v200, v[156:159] offset:12416
	ds_read_b128 v[16:19], v200 offset:12480
	s_waitcnt lgkmcnt(0)
	v_pk_fma_f32 v[160:161], v[160:161], v[248:249], v[16:17] op_sel_hi:[1,0,1]
	v_pk_fma_f32 v[162:163], v[162:163], v[248:249], v[18:19] op_sel_hi:[1,0,1]
	ds_write_b128 v200, v[160:163] offset:12480
	s_waitcnt lgkmcnt(0)
	s_branch .LBB0_1588

.LBB0_2049:
.LBB0_2050:
	v_readfirstlane_b32 s40, v70
	v_readfirstlane_b32 s41, v71
	v_readfirstlane_b32 s62, v72
	v_readfirstlane_b32 s63, v73
	v_and_b32_e32 v248, 15, v181
	v_lshrrev_b32_e32 v249, 4, v181
	v_lshrrev_b32_e32 v248, 2, v248
	v_lshlrev_b32_e32 v249, 2, v249
	v_readlane_b32 s23, v243, 32
	v_mov_b32_e32 v244, 1
	v_lshlrev_b32_e32 v244, v248, v244
	s_mov_b32 s10, 0x3e38aa3b
	s_mov_b32 s11, 0x3e38aa3b
	v_lshlrev_b32_e32 v79, 4, v181
	s_add_i32 s23, s23, s47
	v_add_u32_e32 v247, s23, v248
	v_mad_u64_u32 v[250:251], s[6:7], v247, v212, v[68:69]
	global_load_dwordx4 v[100:103], v[250:251], off
	global_load_dwordx4 v[104:107], v[250:251], off offset:64
	v_add_u32_e32 v249, 4, v247
	v_mad_u64_u32 v[250:251], s[6:7], v249, v212, v[68:69]
	global_load_dwordx4 v[108:111], v[250:251], off
	global_load_dwordx4 v[112:115], v[250:251], off offset:64
	v_add_u32_e32 v249, 8, v247
	v_mad_u64_u32 v[250:251], s[6:7], v249, v212, v[68:69]
	global_load_dwordx4 v[116:119], v[250:251], off
	global_load_dwordx4 v[120:123], v[250:251], off offset:64
	v_add_u32_e32 v249, 12, v247
	v_mad_u64_u32 v[250:251], s[6:7], v249, v212, v[68:69]
	global_load_dwordx4 v[124:127], v[250:251], off
	global_load_dwordx4 v[128:131], v[250:251], off offset:64
	v_and_b32_e32 v248, 15, v181
	v_lshrrev_b32_e32 v249, 4, v181
	v_lshlrev_b32_e32 v198, 6, v248
	v_lshl_add_u32 v198, v249, 2, v198
	v_add_u32_e32 v198, s46, v198
	v_lshl_add_u32 v199, v248, 2, s46
	ds_read_b32 v12, v198 offset:16384
	ds_read_b32 v13, v198 offset:16400
	ds_read_b32 v14, v198 offset:16416
	ds_read_b32 v15, v198 offset:16432
	ds_read_b32 v16, v199 offset:17408
	v_lshl_add_u32 v199, v181, 2, s46
	v_mov_b32_e32 v17, 1
	v_lshlrev_b32_e32 v17, v248, v17
	s_waitcnt lgkmcnt(0)
	v_mul_f32_e32 v81, 0x3fb8aa3b, v81
	ds_write_b32 v199, v11 offset:16384
	ds_write_b32 v199, v11 offset:16640
	ds_write_b32 v199, v11 offset:16896
	ds_write_b32 v199, v11 offset:17152
	v_cmp_lt_i32_e32 vcc, v249, v16
	v_and_b32_e32 v12, 0xff, v12
	v_lshl_add_u32 v12, v12, 2, s46
	v_cndmask_b32_e32 v18, 0, v17, vcc
	ds_or_b32 v12, v18 offset:16384
	v_add_u32_e32 v18, 4, v249
	v_cmp_lt_i32_e32 vcc, v18, v16
	v_and_b32_e32 v13, 0xff, v13
	v_lshl_add_u32 v13, v13, 2, s46
	v_cndmask_b32_e32 v18, 0, v17, vcc
	ds_or_b32 v13, v18 offset:16384
	v_add_u32_e32 v18, 8, v249
	v_cmp_lt_i32_e32 vcc, v18, v16
	v_and_b32_e32 v14, 0xff, v14
	v_lshl_add_u32 v14, v14, 2, s46
	v_cndmask_b32_e32 v18, 0, v17, vcc
	ds_or_b32 v14, v18 offset:16384
	v_add_u32_e32 v18, 12, v249
	v_cmp_lt_i32_e32 vcc, v18, v16
	v_and_b32_e32 v15, 0xff, v15
	v_lshl_add_u32 v15, v15, 2, s46
	v_cndmask_b32_e32 v18, 0, v17, vcc
	ds_or_b32 v15, v18 offset:16384
	s_waitcnt lgkmcnt(0)
	ds_read_b32 v12, v199 offset:16384
	ds_read_b32 v13, v199 offset:16640
	ds_read_b32 v14, v199 offset:16896
	ds_read_b32 v15, v199 offset:17152
	s_mov_b32 s25, 0
	s_waitcnt lgkmcnt(0)
	v_cmp_ne_u32_e64 s[4:5], 0, v12
	v_lshlrev_b32_e32 v16, 16, v12
	v_add_u32_e32 v17, 0, v181
	v_or_b32_e32 v16, v16, v17
	v_mbcnt_lo_u32_b32 v17, s4, 0
	v_mbcnt_hi_u32_b32 v17, s5, v17
	v_add_u32_e32 v17, s25, v17
	v_lshl_add_u32 v17, v17, 2, s46
	v_add_u32_e32 v17, 0x4000, v17
	v_add_u32_e32 v18, 0x4400, v199
	s_bcnt1_i32_b64 s9, s[4:5]
	v_cndmask_b32_e64 v17, v18, v17, s[4:5]
	s_add_i32 s25, s25, s9
	ds_write_b32 v17, v16
	v_cmp_ne_u32_e64 s[4:5], 0, v13
	v_lshlrev_b32_e32 v16, 16, v13
	v_add_u32_e32 v17, 64, v181
	v_or_b32_e32 v16, v16, v17
	v_mbcnt_lo_u32_b32 v17, s4, 0
	v_mbcnt_hi_u32_b32 v17, s5, v17
	v_add_u32_e32 v17, s25, v17
	v_lshl_add_u32 v17, v17, 2, s46
	v_add_u32_e32 v17, 0x4000, v17
	v_add_u32_e32 v18, 0x4400, v199
	s_bcnt1_i32_b64 s9, s[4:5]
	v_cndmask_b32_e64 v17, v18, v17, s[4:5]
	s_add_i32 s25, s25, s9
	ds_write_b32 v17, v16
	v_cmp_ne_u32_e64 s[4:5], 0, v14
	v_lshlrev_b32_e32 v16, 16, v14
	v_add_u32_e32 v17, 128, v181
	v_or_b32_e32 v16, v16, v17
	v_mbcnt_lo_u32_b32 v17, s4, 0
	v_mbcnt_hi_u32_b32 v17, s5, v17
	v_add_u32_e32 v17, s25, v17
	v_lshl_add_u32 v17, v17, 2, s46
	v_add_u32_e32 v17, 0x4000, v17
	v_add_u32_e32 v18, 0x4400, v199
	s_bcnt1_i32_b64 s9, s[4:5]
	v_cndmask_b32_e64 v17, v18, v17, s[4:5]
	s_add_i32 s25, s25, s9
	ds_write_b32 v17, v16
	v_cmp_ne_u32_e64 s[4:5], 0, v15
	v_lshlrev_b32_e32 v16, 16, v15
	v_add_u32_e32 v17, 192, v181
	v_or_b32_e32 v16, v16, v17
	v_mbcnt_lo_u32_b32 v17, s4, 0
	v_mbcnt_hi_u32_b32 v17, s5, v17
	v_add_u32_e32 v17, s25, v17
	v_lshl_add_u32 v17, v17, 2, s46
	v_add_u32_e32 v17, 0x4000, v17
	v_add_u32_e32 v18, 0x4400, v199
	s_bcnt1_i32_b64 s9, s[4:5]
	v_cndmask_b32_e64 v17, v18, v17, s[4:5]
	s_add_i32 s25, s25, s9
	ds_write_b32 v17, v16
	s_waitcnt vmcnt(0)
	v_lshlrev_b32_e32 v245, 16, v100
	v_and_b32_e32 v246, 0xffff0000, v100
	v_mul_f32_e32 v245, 0x41000000, v245
	v_mul_f32_e32 v246, 0x41000000, v246
	v_lshlrev_b32_e32 v248, 16, v101
	v_and_b32_e32 v249, 0xffff0000, v101
	v_cvt_pk_fp8_f32 v164, v245, v246
	v_mul_f32_e32 v248, 0x41000000, v248
	v_mul_f32_e32 v249, 0x41000000, v249
	s_nop 0
	v_cvt_pk_fp8_f32 v164, v248, v249 op_sel:[0,0,1]
	v_lshlrev_b32_e32 v245, 16, v102
	v_and_b32_e32 v246, 0xffff0000, v102
	v_mul_f32_e32 v245, 0x41000000, v245
	v_mul_f32_e32 v246, 0x41000000, v246
	v_lshlrev_b32_e32 v248, 16, v103
	v_and_b32_e32 v249, 0xffff0000, v103
	v_cvt_pk_fp8_f32 v165, v245, v246
	v_mul_f32_e32 v248, 0x41000000, v248
	v_mul_f32_e32 v249, 0x41000000, v249
	s_nop 0
	v_cvt_pk_fp8_f32 v165, v248, v249 op_sel:[0,0,1]
	v_lshlrev_b32_e32 v245, 16, v104
	v_and_b32_e32 v246, 0xffff0000, v104
	v_mul_f32_e32 v245, 0x41000000, v245
	v_mul_f32_e32 v246, 0x41000000, v246
	v_lshlrev_b32_e32 v248, 16, v105
	v_and_b32_e32 v249, 0xffff0000, v105
	v_cvt_pk_fp8_f32 v166, v245, v246
	v_mul_f32_e32 v248, 0x41000000, v248
	v_mul_f32_e32 v249, 0x41000000, v249
	s_nop 0
	v_cvt_pk_fp8_f32 v166, v248, v249 op_sel:[0,0,1]
	v_lshlrev_b32_e32 v245, 16, v106
	v_and_b32_e32 v246, 0xffff0000, v106
	v_mul_f32_e32 v245, 0x41000000, v245
	v_mul_f32_e32 v246, 0x41000000, v246
	v_lshlrev_b32_e32 v248, 16, v107
	v_and_b32_e32 v249, 0xffff0000, v107
	v_cvt_pk_fp8_f32 v167, v245, v246
	v_mul_f32_e32 v248, 0x41000000, v248
	v_mul_f32_e32 v249, 0x41000000, v249
	s_nop 0
	v_cvt_pk_fp8_f32 v167, v248, v249 op_sel:[0,0,1]
	v_lshlrev_b32_e32 v245, 16, v108
	v_and_b32_e32 v246, 0xffff0000, v108
	v_mul_f32_e32 v245, 0x41000000, v245
	v_mul_f32_e32 v246, 0x41000000, v246
	v_lshlrev_b32_e32 v248, 16, v109
	v_and_b32_e32 v249, 0xffff0000, v109
	v_cvt_pk_fp8_f32 v168, v245, v246
	v_mul_f32_e32 v248, 0x41000000, v248
	v_mul_f32_e32 v249, 0x41000000, v249
	s_nop 0
	v_cvt_pk_fp8_f32 v168, v248, v249 op_sel:[0,0,1]
	v_lshlrev_b32_e32 v245, 16, v110
	v_and_b32_e32 v246, 0xffff0000, v110
	v_mul_f32_e32 v245, 0x41000000, v245
	v_mul_f32_e32 v246, 0x41000000, v246
	v_lshlrev_b32_e32 v248, 16, v111
	v_and_b32_e32 v249, 0xffff0000, v111
	v_cvt_pk_fp8_f32 v169, v245, v246
	v_mul_f32_e32 v248, 0x41000000, v248
	v_mul_f32_e32 v249, 0x41000000, v249
	s_nop 0
	v_cvt_pk_fp8_f32 v169, v248, v249 op_sel:[0,0,1]
	v_lshlrev_b32_e32 v245, 16, v112
	v_and_b32_e32 v246, 0xffff0000, v112
	v_mul_f32_e32 v245, 0x41000000, v245
	v_mul_f32_e32 v246, 0x41000000, v246
	v_lshlrev_b32_e32 v248, 16, v113
	v_and_b32_e32 v249, 0xffff0000, v113
	v_cvt_pk_fp8_f32 v170, v245, v246
	v_mul_f32_e32 v248, 0x41000000, v248
	v_mul_f32_e32 v249, 0x41000000, v249
	s_nop 0
	v_cvt_pk_fp8_f32 v170, v248, v249 op_sel:[0,0,1]
	v_lshlrev_b32_e32 v245, 16, v114
	v_and_b32_e32 v246, 0xffff0000, v114
	v_mul_f32_e32 v245, 0x41000000, v245
	v_mul_f32_e32 v246, 0x41000000, v246
	v_lshlrev_b32_e32 v248, 16, v115
	v_and_b32_e32 v249, 0xffff0000, v115
	v_cvt_pk_fp8_f32 v171, v245, v246
	v_mul_f32_e32 v248, 0x41000000, v248
	v_mul_f32_e32 v249, 0x41000000, v249
	s_nop 0
	v_cvt_pk_fp8_f32 v171, v248, v249 op_sel:[0,0,1]
	v_lshlrev_b32_e32 v245, 16, v116
	v_and_b32_e32 v246, 0xffff0000, v116
	v_mul_f32_e32 v245, 0x41000000, v245
	v_mul_f32_e32 v246, 0x41000000, v246
	v_lshlrev_b32_e32 v248, 16, v117
	v_and_b32_e32 v249, 0xffff0000, v117
	v_cvt_pk_fp8_f32 v182, v245, v246
	v_mul_f32_e32 v248, 0x41000000, v248
	v_mul_f32_e32 v249, 0x41000000, v249
	s_nop 0
	v_cvt_pk_fp8_f32 v182, v248, v249 op_sel:[0,0,1]
	v_lshlrev_b32_e32 v245, 16, v118
	v_and_b32_e32 v246, 0xffff0000, v118
	v_mul_f32_e32 v245, 0x41000000, v245
	v_mul_f32_e32 v246, 0x41000000, v246
	v_lshlrev_b32_e32 v248, 16, v119
	v_and_b32_e32 v249, 0xffff0000, v119
	v_cvt_pk_fp8_f32 v183, v245, v246
	v_mul_f32_e32 v248, 0x41000000, v248
	v_mul_f32_e32 v249, 0x41000000, v249
	s_nop 0
	v_cvt_pk_fp8_f32 v183, v248, v249 op_sel:[0,0,1]
	v_lshlrev_b32_e32 v245, 16, v120
	v_and_b32_e32 v246, 0xffff0000, v120
	v_mul_f32_e32 v245, 0x41000000, v245
	v_mul_f32_e32 v246, 0x41000000, v246
	v_lshlrev_b32_e32 v248, 16, v121
	v_and_b32_e32 v249, 0xffff0000, v121
	v_cvt_pk_fp8_f32 v184, v245, v246
	v_mul_f32_e32 v248, 0x41000000, v248
	v_mul_f32_e32 v249, 0x41000000, v249
	s_nop 0
	v_cvt_pk_fp8_f32 v184, v248, v249 op_sel:[0,0,1]
	v_lshlrev_b32_e32 v245, 16, v122
	v_and_b32_e32 v246, 0xffff0000, v122
	v_mul_f32_e32 v245, 0x41000000, v245
	v_mul_f32_e32 v246, 0x41000000, v246
	v_lshlrev_b32_e32 v248, 16, v123
	v_and_b32_e32 v249, 0xffff0000, v123
	v_cvt_pk_fp8_f32 v185, v245, v246
	v_mul_f32_e32 v248, 0x41000000, v248
	v_mul_f32_e32 v249, 0x41000000, v249
	s_nop 0
	v_cvt_pk_fp8_f32 v185, v248, v249 op_sel:[0,0,1]
	v_lshlrev_b32_e32 v245, 16, v124
	v_and_b32_e32 v246, 0xffff0000, v124
	v_mul_f32_e32 v245, 0x41000000, v245
	v_mul_f32_e32 v246, 0x41000000, v246
	v_lshlrev_b32_e32 v248, 16, v125
	v_and_b32_e32 v249, 0xffff0000, v125
	v_cvt_pk_fp8_f32 v186, v245, v246
	v_mul_f32_e32 v248, 0x41000000, v248
	v_mul_f32_e32 v249, 0x41000000, v249
	s_nop 0
	v_cvt_pk_fp8_f32 v186, v248, v249 op_sel:[0,0,1]
	v_lshlrev_b32_e32 v245, 16, v126
	v_and_b32_e32 v246, 0xffff0000, v126
	v_mul_f32_e32 v245, 0x41000000, v245
	v_mul_f32_e32 v246, 0x41000000, v246
	v_lshlrev_b32_e32 v248, 16, v127
	v_and_b32_e32 v249, 0xffff0000, v127
	v_cvt_pk_fp8_f32 v187, v245, v246
	v_mul_f32_e32 v248, 0x41000000, v248
	v_mul_f32_e32 v249, 0x41000000, v249
	s_nop 0
	v_cvt_pk_fp8_f32 v187, v248, v249 op_sel:[0,0,1]
	v_lshlrev_b32_e32 v245, 16, v128
	v_and_b32_e32 v246, 0xffff0000, v128
	v_mul_f32_e32 v245, 0x41000000, v245
	v_mul_f32_e32 v246, 0x41000000, v246
	v_lshlrev_b32_e32 v248, 16, v129
	v_and_b32_e32 v249, 0xffff0000, v129
	v_cvt_pk_fp8_f32 v188, v245, v246
	v_mul_f32_e32 v248, 0x41000000, v248
	v_mul_f32_e32 v249, 0x41000000, v249
	s_nop 0
	v_cvt_pk_fp8_f32 v188, v248, v249 op_sel:[0,0,1]
	v_lshlrev_b32_e32 v245, 16, v130
	v_and_b32_e32 v246, 0xffff0000, v130
	v_mul_f32_e32 v245, 0x41000000, v245
	v_mul_f32_e32 v246, 0x41000000, v246
	v_lshlrev_b32_e32 v248, 16, v131
	v_and_b32_e32 v249, 0xffff0000, v131
	v_cvt_pk_fp8_f32 v189, v245, v246
	v_mul_f32_e32 v248, 0x41000000, v248
	v_mul_f32_e32 v249, 0x41000000, v249
	s_nop 0
	v_cvt_pk_fp8_f32 v189, v248, v249 op_sel:[0,0,1]
	v_mov_b64_e32 v[100:101], 0
	v_mov_b64_e32 v[102:103], 0
	v_mov_b64_e32 v[104:105], 0
	v_mov_b64_e32 v[106:107], 0
	v_mov_b64_e32 v[108:109], 0
	v_mov_b64_e32 v[110:111], 0
	v_mov_b64_e32 v[112:113], 0
	v_mov_b64_e32 v[114:115], 0
	v_mov_b32_e32 v190, 0
	v_mov_b32_e32 v194, 0
	v_mov_b64_e32 v[116:117], 0
	v_mov_b64_e32 v[118:119], 0
	v_mov_b64_e32 v[120:121], 0
	v_mov_b64_e32 v[122:123], 0
	v_mov_b64_e32 v[124:125], 0
	v_mov_b64_e32 v[126:127], 0
	v_mov_b64_e32 v[128:129], 0
	v_mov_b64_e32 v[130:131], 0
	v_mov_b32_e32 v191, 0
	v_mov_b32_e32 v195, 0
	v_mov_b64_e32 v[132:133], 0
	v_mov_b64_e32 v[134:135], 0
	v_mov_b64_e32 v[136:137], 0
	v_mov_b64_e32 v[138:139], 0
	v_mov_b64_e32 v[140:141], 0
	v_mov_b64_e32 v[142:143], 0
	v_mov_b64_e32 v[144:145], 0
	v_mov_b64_e32 v[146:147], 0
	v_mov_b32_e32 v192, 0
	v_mov_b32_e32 v196, 0
	v_mov_b64_e32 v[148:149], 0
	v_mov_b64_e32 v[150:151], 0
	v_mov_b64_e32 v[152:153], 0
	v_mov_b64_e32 v[154:155], 0
	v_mov_b64_e32 v[156:157], 0
	v_mov_b64_e32 v[158:159], 0
	v_mov_b64_e32 v[160:161], 0
	v_mov_b64_e32 v[162:163], 0
	v_mov_b32_e32 v193, 0
	v_mov_b32_e32 v197, 0
	v_mov_b32_e32 v77, 0xff800000
	v_mov_b32_e32 v78, 0xff800000
	s_waitcnt lgkmcnt(0)
	s_mov_b32 s35, 0
	s_lshl_b32 s9, s35, 2
	s_add_i32 s9, s9, s46
	v_mov_b32_e32 v76, s9
	ds_read_b32 v76, v76 offset:16384
	s_add_i32 s50, s25, -1
	s_min_i32 s50, s50, 1
	s_waitcnt lgkmcnt(0)
	v_readfirstlane_b32 s9, v76
	s_and_b32 s38, s9, 0xffff
	s_lshr_b32 s48, s9, 16
	s_lshl_b32 s9, s50, 2
	s_add_i32 s9, s9, s46
	v_mov_b32_e32 v76, s9
	ds_read_b32 v76, v76 offset:16384
	s_lshl_b32 s29, s38, 12
	s_add_u32 s30, s40, s29
	s_addc_u32 s31, s41, 0
	global_load_dwordx4 v[2:5], v79, s[30:31]
	global_load_dwordx4 v[6:9], v79, s[30:31] offset:1024
	global_load_dwordx4 v[12:15], v79, s[30:31] offset:2048
	global_load_dwordx4 v[16:19], v79, s[30:31] offset:3072
	s_lshl_b32 s29, s38, 12
	s_add_u32 s30, s62, s29
	s_addc_u32 s31, s63, 0
	global_load_dwordx4 v[36:39], v79, s[30:31]
	global_load_dwordx4 v[40:43], v79, s[30:31] offset:1024
	global_load_dwordx4 v[44:47], v79, s[30:31] offset:2048
	global_load_dwordx4 v[48:51], v79, s[30:31] offset:3072
	s_waitcnt lgkmcnt(0)
	v_readfirstlane_b32 s9, v76
	s_and_b32 s27, s9, 0xffff
	s_lshr_b32 s8, s9, 16
	s_add_i32 s83, s25, -1
	s_min_i32 s83, s83, 2
	s_lshl_b32 s83, s83, 2
	s_add_i32 s83, s83, s46
	v_mov_b32_e32 v76, s83
	ds_read_b32 v76, v76 offset:16384
	s_lshl_b32 s83, s27, 12
	s_add_u32 s30, s40, s83
	s_addc_u32 s31, s41, 0
	global_load_dwordx4 v[20:23], v79, s[30:31]
	global_load_dwordx4 v[24:27], v79, s[30:31] offset:1024
	global_load_dwordx4 v[28:31], v79, s[30:31] offset:2048
	global_load_dwordx4 v[32:35], v79, s[30:31] offset:3072
	s_waitcnt lgkmcnt(0)
	v_readfirstlane_b32 s9, v76
	s_and_b32 s32, s9, 0xffff
	s_lshr_b32 s55, s9, 16
	v_readfirstlane_b32 s83, v1
	s_bitcmp1_b32 s83, 8
	s_cbranch_scc0 .Lbm3_nostag
	s_setprio 2
	s_sleep 4

.Lbm3_done:
	s_setprio 0
	s_waitcnt vmcnt(0)
	v_and_b32_e32 v245, 15, v181
	v_lshrrev_b32_e32 v246, 4, v181
	v_lshrrev_b32_e32 v247, 2, v245
	v_add_u32_e32 v247, s23, v247
	v_lshlrev_b32_e32 v245, 8, v245
	v_lshl_add_u32 v245, v246, 4, v245
	v_add_u32_e32 v200, s46, v245
	v_mad_u64_u32 v[250:251], s[6:7], v247, v213, v[74:75]
	global_load_dword v252, v[250:251], off offset:4
	v_add_u32_e32 v246, 4, v247
	v_mad_u64_u32 v[250:251], s[6:7], v246, v213, v[74:75]
	global_load_dword v253, v[250:251], off offset:4
	v_add_u32_e32 v246, 8, v247
	v_mad_u64_u32 v[250:251], s[6:7], v246, v213, v[74:75]
	global_load_dword v254, v[250:251], off offset:4
	v_add_u32_e32 v246, 12, v247
	v_mad_u64_u32 v[250:251], s[6:7], v246, v213, v[74:75]
	global_load_dword v255, v[250:251], off offset:4
	v_mov_b32_e32 v199, v194
	s_nop 1
	v_permlane16_swap_b32_e32 v194, v199
	s_nop 0
	v_add_f32_e32 v194, v194, v199
	v_mov_b32_e32 v199, v194
	s_nop 1
	v_permlane32_swap_b32_e32 v194, v199
	s_nop 0
	v_add_f32_e32 v194, v194, v199
	v_max_f32_e32 v194, 0xda24260, v194
	v_mov_b32_e32 v199, v195
	s_nop 1
	v_permlane16_swap_b32_e32 v195, v199
	s_nop 0
	v_add_f32_e32 v195, v195, v199
	v_mov_b32_e32 v199, v195
	s_nop 1
	v_permlane32_swap_b32_e32 v195, v199
	s_nop 0
	v_add_f32_e32 v195, v195, v199
	v_max_f32_e32 v195, 0xda24260, v195
	v_mov_b32_e32 v199, v196
	s_nop 1
	v_permlane16_swap_b32_e32 v196, v199
	s_nop 0
	v_add_f32_e32 v196, v196, v199
	v_mov_b32_e32 v199, v196
	s_nop 1
	v_permlane32_swap_b32_e32 v196, v199
	s_nop 0
	v_add_f32_e32 v196, v196, v199
	v_max_f32_e32 v196, 0xda24260, v196
	v_mov_b32_e32 v199, v197
	s_nop 1
	v_permlane16_swap_b32_e32 v197, v199
	s_nop 0
	v_add_f32_e32 v197, v197, v199
	v_mov_b32_e32 v199, v197
	s_nop 1
	v_permlane32_swap_b32_e32 v197, v199
	s_nop 0
	v_add_f32_e32 v197, v197, v199
	v_max_f32_e32 v197, 0xda24260, v197
	s_waitcnt vmcnt(0)
	v_div_scale_f32 v2, s[6:7], v194, v194, v252
	v_rcp_f32_e32 v3, v2
	s_nop 0
	v_fma_f32 v4, -v2, v3, 1.0
	v_fmac_f32_e32 v3, v4, v3
	v_div_scale_f32 v4, vcc, v252, v194, v252
	v_mul_f32_e32 v5, v4, v3
	v_fma_f32 v6, -v2, v5, v4
	v_fmac_f32_e32 v5, v6, v3
	v_fma_f32 v2, -v2, v5, v4
	v_div_fmas_f32 v2, v2, v3, v5
	v_div_fixup_f32 v248, v2, v194, v252
	ds_read_b128 v[16:19], v200 offset:0
	s_waitcnt lgkmcnt(0)
	v_pk_fma_f32 v[100:101], v[100:101], v[248:249], v[16:17] op_sel_hi:[1,0,1]
	v_pk_fma_f32 v[102:103], v[102:103], v[248:249], v[18:19] op_sel_hi:[1,0,1]
	ds_write_b128 v200, v[100:103] offset:0
	ds_read_b128 v[16:19], v200 offset:64
	s_waitcnt lgkmcnt(0)
	v_pk_fma_f32 v[104:105], v[104:105], v[248:249], v[16:17] op_sel_hi:[1,0,1]
	v_pk_fma_f32 v[106:107], v[106:107], v[248:249], v[18:19] op_sel_hi:[1,0,1]
	ds_write_b128 v200, v[104:107] offset:64
	ds_read_b128 v[16:19], v200 offset:128
	s_waitcnt lgkmcnt(0)
	v_pk_fma_f32 v[108:109], v[108:109], v[248:249], v[16:17] op_sel_hi:[1,0,1]
	v_pk_fma_f32 v[110:111], v[110:111], v[248:249], v[18:19] op_sel_hi:[1,0,1]
	ds_write_b128 v200, v[108:111] offset:128
	ds_read_b128 v[16:19], v200 offset:192
	s_waitcnt lgkmcnt(0)
	v_pk_fma_f32 v[112:113], v[112:113], v[248:249], v[16:17] op_sel_hi:[1,0,1]
	v_pk_fma_f32 v[114:115], v[114:115], v[248:249], v[18:19] op_sel_hi:[1,0,1]
	ds_write_b128 v200, v[112:115] offset:192
	v_div_scale_f32 v2, s[6:7], v195, v195, v253
	v_rcp_f32_e32 v3, v2
	s_nop 0
	v_fma_f32 v4, -v2, v3, 1.0
	v_fmac_f32_e32 v3, v4, v3
	v_div_scale_f32 v4, vcc, v253, v195, v253
	v_mul_f32_e32 v5, v4, v3
	v_fma_f32 v6, -v2, v5, v4
	v_fmac_f32_e32 v5, v6, v3
	v_fma_f32 v2, -v2, v5, v4
	v_div_fmas_f32 v2, v2, v3, v5
	v_div_fixup_f32 v248, v2, v195, v253
	ds_read_b128 v[16:19], v200 offset:4096
	s_waitcnt lgkmcnt(0)
	v_pk_fma_f32 v[116:117], v[116:117], v[248:249], v[16:17] op_sel_hi:[1,0,1]
	v_pk_fma_f32 v[118:119], v[118:119], v[248:249], v[18:19] op_sel_hi:[1,0,1]
	ds_write_b128 v200, v[116:119] offset:4096
	ds_read_b128 v[16:19], v200 offset:4160
	s_waitcnt lgkmcnt(0)
	v_pk_fma_f32 v[120:121], v[120:121], v[248:249], v[16:17] op_sel_hi:[1,0,1]
	v_pk_fma_f32 v[122:123], v[122:123], v[248:249], v[18:19] op_sel_hi:[1,0,1]
	ds_write_b128 v200, v[120:123] offset:4160
	ds_read_b128 v[16:19], v200 offset:4224
	s_waitcnt lgkmcnt(0)
	v_pk_fma_f32 v[124:125], v[124:125], v[248:249], v[16:17] op_sel_hi:[1,0,1]
	v_pk_fma_f32 v[126:127], v[126:127], v[248:249], v[18:19] op_sel_hi:[1,0,1]
	ds_write_b128 v200, v[124:127] offset:4224
	ds_read_b128 v[16:19], v200 offset:4288
	s_waitcnt lgkmcnt(0)
	v_pk_fma_f32 v[128:129], v[128:129], v[248:249], v[16:17] op_sel_hi:[1,0,1]
	v_pk_fma_f32 v[130:131], v[130:131], v[248:249], v[18:19] op_sel_hi:[1,0,1]
	ds_write_b128 v200, v[128:131] offset:4288
	v_div_scale_f32 v2, s[6:7], v196, v196, v254
	v_rcp_f32_e32 v3, v2
	s_nop 0
	v_fma_f32 v4, -v2, v3, 1.0
	v_fmac_f32_e32 v3, v4, v3
	v_div_scale_f32 v4, vcc, v254, v196, v254
	v_mul_f32_e32 v5, v4, v3
	v_fma_f32 v6, -v2, v5, v4
	v_fmac_f32_e32 v5, v6, v3
	v_fma_f32 v2, -v2, v5, v4
	v_div_fmas_f32 v2, v2, v3, v5
	v_div_fixup_f32 v248, v2, v196, v254
	ds_read_b128 v[16:19], v200 offset:8192
	s_waitcnt lgkmcnt(0)
	v_pk_fma_f32 v[132:133], v[132:133], v[248:249], v[16:17] op_sel_hi:[1,0,1]
	v_pk_fma_f32 v[134:135], v[134:135], v[248:249], v[18:19] op_sel_hi:[1,0,1]
	ds_write_b128 v200, v[132:135] offset:8192
	ds_read_b128 v[16:19], v200 offset:8256
	s_waitcnt lgkmcnt(0)
	v_pk_fma_f32 v[136:137], v[136:137], v[248:249], v[16:17] op_sel_hi:[1,0,1]
	v_pk_fma_f32 v[138:139], v[138:139], v[248:249], v[18:19] op_sel_hi:[1,0,1]
	ds_write_b128 v200, v[136:139] offset:8256
	ds_read_b128 v[16:19], v200 offset:8320
	s_waitcnt lgkmcnt(0)
	v_pk_fma_f32 v[140:141], v[140:141], v[248:249], v[16:17] op_sel_hi:[1,0,1]
	v_pk_fma_f32 v[142:143], v[142:143], v[248:249], v[18:19] op_sel_hi:[1,0,1]
	ds_write_b128 v200, v[140:143] offset:8320
	ds_read_b128 v[16:19], v200 offset:8384
	s_waitcnt lgkmcnt(0)
	v_pk_fma_f32 v[144:145], v[144:145], v[248:249], v[16:17] op_sel_hi:[1,0,1]
	v_pk_fma_f32 v[146:147], v[146:147], v[248:249], v[18:19] op_sel_hi:[1,0,1]
	ds_write_b128 v200, v[144:147] offset:8384
	v_div_scale_f32 v2, s[6:7], v197, v197, v255
	v_rcp_f32_e32 v3, v2
	s_nop 0
	v_fma_f32 v4, -v2, v3, 1.0
	v_fmac_f32_e32 v3, v4, v3
	v_div_scale_f32 v4, vcc, v255, v197, v255
	v_mul_f32_e32 v5, v4, v3
	v_fma_f32 v6, -v2, v5, v4
	v_fmac_f32_e32 v5, v6, v3
	v_fma_f32 v2, -v2, v5, v4
	v_div_fmas_f32 v2, v2, v3, v5
	v_div_fixup_f32 v248, v2, v197, v255
	ds_read_b128 v[16:19], v200 offset:12288
	s_waitcnt lgkmcnt(0)
	v_pk_fma_f32 v[148:149], v[148:149], v[248:249], v[16:17] op_sel_hi:[1,0,1]
	v_pk_fma_f32 v[150:151], v[150:151], v[248:249], v[18:19] op_sel_hi:[1,0,1]
	ds_write_b128 v200, v[148:151] offset:12288
	ds_read_b128 v[16:19], v200 offset:12352
	s_waitcnt lgkmcnt(0)
	v_pk_fma_f32 v[152:153], v[152:153], v[248:249], v[16:17] op_sel_hi:[1,0,1]
	v_pk_fma_f32 v[154:155], v[154:155], v[248:249], v[18:19] op_sel_hi:[1,0,1]
	ds_write_b128 v200, v[152:155] offset:12352
	ds_read_b128 v[16:19], v200 offset:12416
	s_waitcnt lgkmcnt(0)
	v_pk_fma_f32 v[156:157], v[156:157], v[248:249], v[16:17] op_sel_hi:[1,0,1]
	v_pk_fma_f32 v[158:159], v[158:159], v[248:249], v[18:19] op_sel_hi:[1,0,1]
	ds_write_b128 v200, v[156:159] offset:12416
	ds_read_b128 v[16:19], v200 offset:12480
	s_waitcnt lgkmcnt(0)
	v_pk_fma_f32 v[160:161], v[160:161], v[248:249], v[16:17] op_sel_hi:[1,0,1]
	v_pk_fma_f32 v[162:163], v[162:163], v[248:249], v[18:19] op_sel_hi:[1,0,1]
	ds_write_b128 v200, v[160:163] offset:12480
	s_waitcnt lgkmcnt(0)
	s_branch .LBB0_2088
